# attention tile epilogue: gate loads issued 16 at a time (two waits) instead of 32 serialized load-silu-store round trips
# baseline (speedup 1.0000x reference)
; __device__ __forceinline__ float bf2f(bf16_t v) { return __uint_as_float(((unsigned)v) << 16); }
; __device__ __forceinline__ bf16_t f2bf(float f) { return (bf16_t)(pack2(f, 0.f) & 0xffffu); }
; __device__ __forceinline__ float frcp(float x) { return __builtin_amdgcn_rcpf(x); }
; __device__ __forceinline__ float siluf_(float x) { return x * frcp(1.f + __expf(-x)); }
; __device__ __forceinline__ void attn_tile(const Params& p, int l, int tile, unsigned char* smem) {
;     ...
; #pragma unroll
;   for (int mt = 0; mt < 2; ++mt) {
;     const int qi0 = (2 * w + mt) * 16;
; #pragma unroll
;     for (int j = 0; j < 4; ++j) {
;       const size_t r = rowq0 + qi0 + fq * 4 + j;
;       const float inv = frcp(ls[mt][j]);
; #pragma unroll
;       for (int nt = 0; nt < 4; ++nt) {
;         const int dc = nt * 16 + fr;
;         const float gt = bf2f(p.PA[r * 1024 + 640 + head * 64 + dc]);
;         p.PA[r * 1024 + head * 64 + dc] = f2bf(o[mt][nt][j] * inv * siluf_(gt));
;       }
;     }
;   }
.LBB0_506:
	s_waitcnt vmcnt(1)
	v_or_b32_e32 v40, s28, v49
	v_readlane_b32 s0, v251, 48
	v_readlane_b32 s1, v251, 49
	v_readlane_b32 s2, v251, 50
	v_readlane_b32 s3, v251, 51
	v_readlane_b32 s4, v251, 52
	v_readlane_b32 s5, v251, 53
	v_readlane_b32 s6, v251, 54
	v_readlane_b32 s7, v251, 55
	v_readlane_b32 s8, v251, 56
	v_readlane_b32 s9, v251, 57
	v_readlane_b32 s10, v251, 58
	v_readlane_b32 s11, v251, 59
	v_readlane_b32 s12, v251, 60
	v_readlane_b32 s13, v251, 61
	v_readlane_b32 s14, v251, 62
	v_readlane_b32 s15, v251, 63
	s_add_u32 s2, s8, s54
	s_addc_u32 s3, s9, s55
	v_add_u32_e32 v146, v40, v98
	v_add_u32_e32 v147, v40, v96
	v_lshlrev_b32_e32 v146, 11, v146
	v_lshlrev_b32_e32 v147, 11, v147
	v_add_u32_e32 v120, 0x1000, v146
	v_add_u32_e32 v121, 0x1000, v147
	s_waitcnt vmcnt(0)
	v_lshl_add_u32 v126, v104, 1, v146
	v_lshl_add_u32 v127, v52, 1, v146
	v_lshl_add_u32 v128, v50, 1, v146
	v_lshl_add_u32 v129, v48, 1, v146
	v_lshl_add_u32 v130, v104, 1, v120
	v_lshl_add_u32 v131, v52, 1, v120
	v_lshl_add_u32 v132, v50, 1, v120
	v_lshl_add_u32 v133, v48, 1, v120
	v_lshl_add_u32 v134, v104, 1, v147
	v_lshl_add_u32 v135, v52, 1, v147
	v_lshl_add_u32 v136, v50, 1, v147
	v_lshl_add_u32 v137, v48, 1, v147
	v_lshl_add_u32 v138, v104, 1, v121
	v_lshl_add_u32 v139, v52, 1, v121
	v_lshl_add_u32 v140, v50, 1, v121
	v_lshl_add_u32 v141, v48, 1, v121
	global_load_ushort v32, v126, s[2:3] offset:1280
	global_load_ushort v33, v127, s[2:3] offset:1280
	global_load_ushort v34, v128, s[2:3] offset:1280
	global_load_ushort v35, v129, s[2:3] offset:1280
	global_load_ushort v36, v126, s[2:3] offset:3328
	global_load_ushort v37, v127, s[2:3] offset:3328
	global_load_ushort v38, v128, s[2:3] offset:3328
	global_load_ushort v39, v129, s[2:3] offset:3328
	global_load_ushort v42, v130, s[2:3] offset:1280
	global_load_ushort v43, v131, s[2:3] offset:1280
	global_load_ushort v44, v132, s[2:3] offset:1280
	global_load_ushort v45, v133, s[2:3] offset:1280
	global_load_ushort v46, v130, s[2:3] offset:3328
	global_load_ushort v47, v131, s[2:3] offset:3328
	global_load_ushort v54, v132, s[2:3] offset:3328
	global_load_ushort v55, v133, s[2:3] offset:3328
	v_rcp_f32_e32 v56, v71
	v_rcp_f32_e32 v57, v70
	v_rcp_f32_e32 v58, v69
	v_rcp_f32_e32 v59, v68
	v_mul_f32_e32 v28, v56, v28
	v_mul_f32_e32 v20, v56, v20
	v_mul_f32_e32 v16, v56, v16
	v_mul_f32_e32 v24, v56, v24
	v_mul_f32_e32 v29, v57, v29
	v_mul_f32_e32 v21, v57, v21
	v_mul_f32_e32 v17, v57, v17
	v_mul_f32_e32 v25, v57, v25
	v_mul_f32_e32 v30, v58, v30
	v_mul_f32_e32 v22, v58, v22
	v_mul_f32_e32 v18, v58, v18
	v_mul_f32_e32 v26, v58, v26
	v_mul_f32_e32 v31, v59, v31
	v_mul_f32_e32 v23, v59, v23
	v_mul_f32_e32 v19, v59, v19
	v_mul_f32_e32 v27, v59, v27
	s_waitcnt vmcnt(0)
	v_lshlrev_b32_e32 v32, 16, v32
	v_lshlrev_b32_e32 v33, 16, v33
	v_lshlrev_b32_e32 v34, 16, v34
	v_lshlrev_b32_e32 v35, 16, v35
	v_lshlrev_b32_e32 v36, 16, v36
	v_lshlrev_b32_e32 v37, 16, v37
	v_lshlrev_b32_e32 v38, 16, v38
	v_lshlrev_b32_e32 v39, 16, v39
	v_mul_f32_e32 v120, 0xbfb8aa3b, v32
	v_mul_f32_e32 v121, 0xbfb8aa3b, v33
	v_mul_f32_e32 v122, 0xbfb8aa3b, v34
	v_mul_f32_e32 v123, 0xbfb8aa3b, v35
	v_mul_f32_e32 v142, 0xbfb8aa3b, v36
	v_mul_f32_e32 v143, 0xbfb8aa3b, v37
	v_mul_f32_e32 v144, 0xbfb8aa3b, v38
	v_mul_f32_e32 v145, 0xbfb8aa3b, v39
	v_exp_f32_e32 v120, v120
	v_exp_f32_e32 v121, v121
	v_exp_f32_e32 v122, v122
	v_exp_f32_e32 v123, v123
	v_exp_f32_e32 v142, v142
	v_exp_f32_e32 v143, v143
	v_exp_f32_e32 v144, v144
	v_exp_f32_e32 v145, v145
	v_add_f32_e32 v120, 1.0, v120
	v_add_f32_e32 v121, 1.0, v121
	v_add_f32_e32 v122, 1.0, v122
	v_add_f32_e32 v123, 1.0, v123
	v_add_f32_e32 v142, 1.0, v142
	v_add_f32_e32 v143, 1.0, v143
	v_add_f32_e32 v144, 1.0, v144
	v_add_f32_e32 v145, 1.0, v145
	v_rcp_f32_e32 v120, v120
	v_rcp_f32_e32 v121, v121
	v_rcp_f32_e32 v122, v122
	v_rcp_f32_e32 v123, v123
	v_rcp_f32_e32 v142, v142
	v_rcp_f32_e32 v143, v143
	v_rcp_f32_e32 v144, v144
	v_rcp_f32_e32 v145, v145
	v_mul_f32_e32 v32, v120, v32
	v_mul_f32_e32 v33, v121, v33
	v_mul_f32_e32 v34, v122, v34
	v_mul_f32_e32 v35, v123, v35
	v_mul_f32_e32 v36, v142, v36
	v_mul_f32_e32 v37, v143, v37
	v_mul_f32_e32 v38, v144, v38
	v_mul_f32_e32 v39, v145, v39
	v_mul_f32_e32 v28, v28, v32
	v_mul_f32_e32 v20, v20, v33
	v_mul_f32_e32 v16, v16, v34
	v_mul_f32_e32 v24, v24, v35
	v_mul_f32_e32 v29, v29, v36
	v_mul_f32_e32 v21, v21, v37
	v_mul_f32_e32 v17, v17, v38
	v_mul_f32_e32 v25, v25, v39
	v_cvt_pk_bf16_f32 v28, v28, v28
	v_cvt_pk_bf16_f32 v20, v20, v20
	v_cvt_pk_bf16_f32 v16, v16, v16
	v_cvt_pk_bf16_f32 v24, v24, v24
	v_cvt_pk_bf16_f32 v29, v29, v29
	v_cvt_pk_bf16_f32 v21, v21, v21
	v_cvt_pk_bf16_f32 v17, v17, v17
	v_cvt_pk_bf16_f32 v25, v25, v25
	global_store_short v126, v28, s[2:3]
	global_store_short v127, v20, s[2:3]
	global_store_short v128, v16, s[2:3]
	global_store_short v129, v24, s[2:3]
	global_store_short v126, v29, s[2:3] offset:2048
	global_store_short v127, v21, s[2:3] offset:2048
	global_store_short v128, v17, s[2:3] offset:2048
	global_store_short v129, v25, s[2:3] offset:2048
	v_lshlrev_b32_e32 v42, 16, v42
	v_lshlrev_b32_e32 v43, 16, v43
	v_lshlrev_b32_e32 v44, 16, v44
	v_lshlrev_b32_e32 v45, 16, v45
	v_lshlrev_b32_e32 v46, 16, v46
	v_lshlrev_b32_e32 v47, 16, v47
	v_lshlrev_b32_e32 v54, 16, v54
	v_lshlrev_b32_e32 v55, 16, v55
	v_mul_f32_e32 v120, 0xbfb8aa3b, v42
	v_mul_f32_e32 v121, 0xbfb8aa3b, v43
	v_mul_f32_e32 v122, 0xbfb8aa3b, v44
	v_mul_f32_e32 v123, 0xbfb8aa3b, v45
	v_mul_f32_e32 v142, 0xbfb8aa3b, v46
	v_mul_f32_e32 v143, 0xbfb8aa3b, v47
	v_mul_f32_e32 v144, 0xbfb8aa3b, v54
	v_mul_f32_e32 v145, 0xbfb8aa3b, v55
	v_exp_f32_e32 v120, v120
	v_exp_f32_e32 v121, v121
; __device__ __forceinline__ float bf2f(bf16_t v) { return __uint_as_float(((unsigned)v) << 16); }
; __device__ __forceinline__ bf16_t f2bf(float f) { return (bf16_t)(pack2(f, 0.f) & 0xffffu); }
; __device__ __forceinline__ float frcp(float x) { return __builtin_amdgcn_rcpf(x); }
; __device__ __forceinline__ float siluf_(float x) { return x * frcp(1.f + __expf(-x)); }
; __device__ __forceinline__ void attn_tile(const Params& p, int l, int tile, unsigned char* smem) {
;     ...
; #pragma unroll
;   for (int mt = 0; mt < 2; ++mt) {
;     const int qi0 = (2 * w + mt) * 16;
; #pragma unroll
;     for (int j = 0; j < 4; ++j) {
;       const size_t r = rowq0 + qi0 + fq * 4 + j;
;       const float inv = frcp(ls[mt][j]);
; #pragma unroll
;       for (int nt = 0; nt < 4; ++nt) {
;         const int dc = nt * 16 + fr;
;         const float gt = bf2f(p.PA[r * 1024 + 640 + head * 64 + dc]);
;         p.PA[r * 1024 + head * 64 + dc] = f2bf(o[mt][nt][j] * inv * siluf_(gt));
;       }
;     }
;   }
	v_exp_f32_e32 v122, v122
	v_exp_f32_e32 v123, v123
	v_exp_f32_e32 v142, v142
	v_exp_f32_e32 v143, v143
	v_exp_f32_e32 v144, v144
	v_exp_f32_e32 v145, v145
	v_add_f32_e32 v120, 1.0, v120
	v_add_f32_e32 v121, 1.0, v121
	v_add_f32_e32 v122, 1.0, v122
	v_add_f32_e32 v123, 1.0, v123
	v_add_f32_e32 v142, 1.0, v142
	v_add_f32_e32 v143, 1.0, v143
	v_add_f32_e32 v144, 1.0, v144
	v_add_f32_e32 v145, 1.0, v145
	v_rcp_f32_e32 v120, v120
	v_rcp_f32_e32 v121, v121
	v_rcp_f32_e32 v122, v122
	v_rcp_f32_e32 v123, v123
	v_rcp_f32_e32 v142, v142
	v_rcp_f32_e32 v143, v143
	v_rcp_f32_e32 v144, v144
	v_rcp_f32_e32 v145, v145
	v_mul_f32_e32 v42, v120, v42
	v_mul_f32_e32 v43, v121, v43
	v_mul_f32_e32 v44, v122, v44
	v_mul_f32_e32 v45, v123, v45
	v_mul_f32_e32 v46, v142, v46
	v_mul_f32_e32 v47, v143, v47
	v_mul_f32_e32 v54, v144, v54
	v_mul_f32_e32 v55, v145, v55
	v_mul_f32_e32 v30, v30, v42
	v_mul_f32_e32 v22, v22, v43
	v_mul_f32_e32 v18, v18, v44
	v_mul_f32_e32 v26, v26, v45
	v_mul_f32_e32 v31, v31, v46
	v_mul_f32_e32 v23, v23, v47
	v_mul_f32_e32 v19, v19, v54
	v_mul_f32_e32 v27, v27, v55
	v_cvt_pk_bf16_f32 v30, v30, v30
	v_cvt_pk_bf16_f32 v22, v22, v22
	v_cvt_pk_bf16_f32 v18, v18, v18
	v_cvt_pk_bf16_f32 v26, v26, v26
	v_cvt_pk_bf16_f32 v31, v31, v31
	v_cvt_pk_bf16_f32 v23, v23, v23
	v_cvt_pk_bf16_f32 v19, v19, v19
	v_cvt_pk_bf16_f32 v27, v27, v27
	global_store_short v130, v30, s[2:3]
	global_store_short v131, v22, s[2:3]
	global_store_short v132, v18, s[2:3]
	global_store_short v133, v26, s[2:3]
	global_store_short v130, v31, s[2:3] offset:2048
	global_store_short v131, v23, s[2:3] offset:2048
	global_store_short v132, v19, s[2:3] offset:2048
	global_store_short v133, v27, s[2:3] offset:2048
	global_load_ushort v32, v134, s[2:3] offset:1280
	global_load_ushort v33, v135, s[2:3] offset:1280
	global_load_ushort v34, v136, s[2:3] offset:1280
	global_load_ushort v35, v137, s[2:3] offset:1280
	global_load_ushort v36, v134, s[2:3] offset:3328
	global_load_ushort v37, v135, s[2:3] offset:3328
	global_load_ushort v38, v136, s[2:3] offset:3328
	global_load_ushort v39, v137, s[2:3] offset:3328
	global_load_ushort v42, v138, s[2:3] offset:1280
	global_load_ushort v43, v139, s[2:3] offset:1280
	global_load_ushort v44, v140, s[2:3] offset:1280
	global_load_ushort v45, v141, s[2:3] offset:1280
	global_load_ushort v46, v138, s[2:3] offset:3328
	global_load_ushort v47, v139, s[2:3] offset:3328
	global_load_ushort v54, v140, s[2:3] offset:3328
	global_load_ushort v55, v141, s[2:3] offset:3328
	v_rcp_f32_e32 v56, v67
	v_rcp_f32_e32 v57, v66
	v_rcp_f32_e32 v58, v64
	v_rcp_f32_e32 v59, v65
	v_mul_f32_e32 v12, v56, v12
	v_mul_f32_e32 v8, v56, v8
	v_mul_f32_e32 v4, v56, v4
	v_mul_f32_e32 v0, v56, v0
	v_mul_f32_e32 v13, v57, v13
	v_mul_f32_e32 v9, v57, v9
	v_mul_f32_e32 v5, v57, v5
	v_mul_f32_e32 v1, v57, v1
	v_mul_f32_e32 v14, v58, v14
	v_mul_f32_e32 v10, v58, v10
	v_mul_f32_e32 v6, v58, v6
	v_mul_f32_e32 v2, v58, v2
	v_mul_f32_e32 v15, v59, v15
	v_mul_f32_e32 v11, v59, v11
	v_mul_f32_e32 v7, v59, v7
	v_mul_f32_e32 v3, v59, v3
	s_waitcnt vmcnt(0)
; __device__ __forceinline__ float bf2f(bf16_t v) { return __uint_as_float(((unsigned)v) << 16); }
; __device__ __forceinline__ bf16_t f2bf(float f) { return (bf16_t)(pack2(f, 0.f) & 0xffffu); }
; __device__ __forceinline__ float frcp(float x) { return __builtin_amdgcn_rcpf(x); }
; __device__ __forceinline__ float siluf_(float x) { return x * frcp(1.f + __expf(-x)); }
; __device__ __forceinline__ void attn_tile(const Params& p, int l, int tile, unsigned char* smem) {
;     ...
; #pragma unroll
;   for (int mt = 0; mt < 2; ++mt) {
;     const int qi0 = (2 * w + mt) * 16;
; #pragma unroll
;     for (int j = 0; j < 4; ++j) {
;       const size_t r = rowq0 + qi0 + fq * 4 + j;
;       const float inv = frcp(ls[mt][j]);
; #pragma unroll
;       for (int nt = 0; nt < 4; ++nt) {
;         const int dc = nt * 16 + fr;
;         const float gt = bf2f(p.PA[r * 1024 + 640 + head * 64 + dc]);
;         p.PA[r * 1024 + head * 64 + dc] = f2bf(o[mt][nt][j] * inv * siluf_(gt));
;       }
;     }
;   }
	v_lshlrev_b32_e32 v32, 16, v32
	v_lshlrev_b32_e32 v33, 16, v33
	v_lshlrev_b32_e32 v34, 16, v34
	v_lshlrev_b32_e32 v35, 16, v35
	v_lshlrev_b32_e32 v36, 16, v36
	v_lshlrev_b32_e32 v37, 16, v37
	v_lshlrev_b32_e32 v38, 16, v38
	v_lshlrev_b32_e32 v39, 16, v39
	v_mul_f32_e32 v120, 0xbfb8aa3b, v32
	v_mul_f32_e32 v121, 0xbfb8aa3b, v33
	v_mul_f32_e32 v122, 0xbfb8aa3b, v34
	v_mul_f32_e32 v123, 0xbfb8aa3b, v35
	v_mul_f32_e32 v142, 0xbfb8aa3b, v36
	v_mul_f32_e32 v143, 0xbfb8aa3b, v37
	v_mul_f32_e32 v144, 0xbfb8aa3b, v38
	v_mul_f32_e32 v145, 0xbfb8aa3b, v39
	v_exp_f32_e32 v120, v120
	v_exp_f32_e32 v121, v121
	v_exp_f32_e32 v122, v122
	v_exp_f32_e32 v123, v123
	v_exp_f32_e32 v142, v142
	v_exp_f32_e32 v143, v143
	v_exp_f32_e32 v144, v144
	v_exp_f32_e32 v145, v145
	v_add_f32_e32 v120, 1.0, v120
	v_add_f32_e32 v121, 1.0, v121
	v_add_f32_e32 v122, 1.0, v122
	v_add_f32_e32 v123, 1.0, v123
	v_add_f32_e32 v142, 1.0, v142
	v_add_f32_e32 v143, 1.0, v143
	v_add_f32_e32 v144, 1.0, v144
	v_add_f32_e32 v145, 1.0, v145
	v_rcp_f32_e32 v120, v120
	v_rcp_f32_e32 v121, v121
	v_rcp_f32_e32 v122, v122
	v_rcp_f32_e32 v123, v123
	v_rcp_f32_e32 v142, v142
	v_rcp_f32_e32 v143, v143
	v_rcp_f32_e32 v144, v144
	v_rcp_f32_e32 v145, v145
	v_mul_f32_e32 v32, v120, v32
	v_mul_f32_e32 v33, v121, v33
	v_mul_f32_e32 v34, v122, v34
	v_mul_f32_e32 v35, v123, v35
	v_mul_f32_e32 v36, v142, v36
	v_mul_f32_e32 v37, v143, v37
	v_mul_f32_e32 v38, v144, v38
	v_mul_f32_e32 v39, v145, v39
	v_mul_f32_e32 v12, v12, v32
	v_mul_f32_e32 v8, v8, v33
	v_mul_f32_e32 v4, v4, v34
	v_mul_f32_e32 v0, v0, v35
	v_mul_f32_e32 v13, v13, v36
	v_mul_f32_e32 v9, v9, v37
	v_mul_f32_e32 v5, v5, v38
	v_mul_f32_e32 v1, v1, v39
	v_cvt_pk_bf16_f32 v12, v12, v12
	v_cvt_pk_bf16_f32 v8, v8, v8
	v_cvt_pk_bf16_f32 v4, v4, v4
	v_cvt_pk_bf16_f32 v0, v0, v0
	v_cvt_pk_bf16_f32 v13, v13, v13
	v_cvt_pk_bf16_f32 v9, v9, v9
	v_cvt_pk_bf16_f32 v5, v5, v5
	v_cvt_pk_bf16_f32 v1, v1, v1
	global_store_short v134, v12, s[2:3]
	global_store_short v135, v8, s[2:3]
	global_store_short v136, v4, s[2:3]
	global_store_short v137, v0, s[2:3]
	global_store_short v134, v13, s[2:3] offset:2048
	global_store_short v135, v9, s[2:3] offset:2048
	global_store_short v136, v5, s[2:3] offset:2048
	global_store_short v137, v1, s[2:3] offset:2048
	v_lshlrev_b32_e32 v42, 16, v42
	v_lshlrev_b32_e32 v43, 16, v43
	v_lshlrev_b32_e32 v44, 16, v44
	v_lshlrev_b32_e32 v45, 16, v45
	v_lshlrev_b32_e32 v46, 16, v46
	v_lshlrev_b32_e32 v47, 16, v47
	v_lshlrev_b32_e32 v54, 16, v54
	v_lshlrev_b32_e32 v55, 16, v55
	v_mul_f32_e32 v120, 0xbfb8aa3b, v42
	v_mul_f32_e32 v121, 0xbfb8aa3b, v43
	v_mul_f32_e32 v122, 0xbfb8aa3b, v44
	v_mul_f32_e32 v123, 0xbfb8aa3b, v45
	v_mul_f32_e32 v142, 0xbfb8aa3b, v46
	v_mul_f32_e32 v143, 0xbfb8aa3b, v47
	v_mul_f32_e32 v144, 0xbfb8aa3b, v54
	v_mul_f32_e32 v145, 0xbfb8aa3b, v55
	v_exp_f32_e32 v120, v120
	v_exp_f32_e32 v121, v121
	v_exp_f32_e32 v122, v122
	v_exp_f32_e32 v123, v123
	v_exp_f32_e32 v142, v142
	v_exp_f32_e32 v143, v143
	v_exp_f32_e32 v144, v144
	v_exp_f32_e32 v145, v145
	v_add_f32_e32 v120, 1.0, v120
	v_add_f32_e32 v121, 1.0, v121
	v_add_f32_e32 v122, 1.0, v122
	v_add_f32_e32 v123, 1.0, v123
	v_add_f32_e32 v142, 1.0, v142
	v_add_f32_e32 v143, 1.0, v143
	v_add_f32_e32 v144, 1.0, v144
	v_add_f32_e32 v145, 1.0, v145
	v_rcp_f32_e32 v120, v120
	v_rcp_f32_e32 v121, v121
	v_rcp_f32_e32 v122, v122
	v_rcp_f32_e32 v123, v123
	v_rcp_f32_e32 v142, v142
	v_rcp_f32_e32 v143, v143
	v_rcp_f32_e32 v144, v144
	v_rcp_f32_e32 v145, v145
	v_mul_f32_e32 v42, v120, v42
	v_mul_f32_e32 v43, v121, v43
	v_mul_f32_e32 v44, v122, v44
	v_mul_f32_e32 v45, v123, v45
	v_mul_f32_e32 v46, v142, v46
	v_mul_f32_e32 v47, v143, v47
	v_mul_f32_e32 v54, v144, v54
	v_mul_f32_e32 v55, v145, v55
	v_mul_f32_e32 v14, v14, v42
	v_mul_f32_e32 v10, v10, v43
	v_mul_f32_e32 v6, v6, v44
	v_mul_f32_e32 v2, v2, v45
	v_mul_f32_e32 v15, v15, v46
	v_mul_f32_e32 v11, v11, v47
	v_mul_f32_e32 v7, v7, v54
	v_mul_f32_e32 v3, v3, v55
	v_cvt_pk_bf16_f32 v14, v14, v14
	v_cvt_pk_bf16_f32 v10, v10, v10
	v_cvt_pk_bf16_f32 v6, v6, v6
	v_cvt_pk_bf16_f32 v2, v2, v2
	v_cvt_pk_bf16_f32 v15, v15, v15
	v_cvt_pk_bf16_f32 v11, v11, v11
	v_cvt_pk_bf16_f32 v7, v7, v7
	v_cvt_pk_bf16_f32 v3, v3, v3
	global_store_short v138, v14, s[2:3]
	global_store_short v139, v10, s[2:3]
	global_store_short v140, v6, s[2:3]
	global_store_short v141, v2, s[2:3]
	global_store_short v138, v15, s[2:3] offset:2048
	global_store_short v139, v11, s[2:3] offset:2048
	global_store_short v140, v7, s[2:3] offset:2048
	global_store_short v141, v3, s[2:3] offset:2048
	s_mov_b64 s[2:3], 0x1500
	s_mov_b64 s[4:5], 0x1d00
	s_mov_b64 s[6:7], 0x1800
	s_mov_b64 s[44:45], 0
	s_mov_b64 s[0:1], 0x1000
	s_barrier
